# G2 (p_a/p_b GEMM) mid-K rescale and epilogue: gate loads batched instead of one serialized round trip per 16-row group
# speedup vs baseline: 1.0085x; 1.0085x over previous
; __device__ __forceinline__ float bflo(unsigned w) { return __uint_as_float(w << 16); }
; __device__ __forceinline__ float bfhi(unsigned w) { return __uint_as_float(w & 0xffff0000u); }
;     __device__ __forceinline__ void mid(f32x4 (&acc)[2][2][4][2], const Unit& u, int wr, int wc, int fr, int fq) const {
;         int row0 = u.pm * BM + wr * 64 + fr, col0 = u.pn * BM + wc * 32 + 8 * fq;
;         asm volatile("" : "+v"(row0), "+v"(col0));
; #pragma unroll
;         for (int ai = 0; ai < 2; ++ai)
; #pragma unroll
;             for (int m = 0; m < 4; ++m) { const size_t row = (size_t)(row0 + ai * HALF + m * 16);
; #pragma unroll
;                 for (int bj = 0; bj < 2; ++bj) { const int col = col0 + bj * HALF;
;                     const u32x4 ga = *(const u32x4*)(P + row * LDP + PC_GA + col), gb = *(const u32x4*)(P + row * LDP + PC_GB + col);
; #pragma unroll
;                     for (int j = 0; j < 2; ++j) {
;                         acc[ai][bj][m][0][2 * j] *= bflo(ga[j]) * __builtin_amdgcn_rcpf(bflo(gb[j])); acc[ai][bj][m][0][2 * j + 1] *= bfhi(ga[j]) * __builtin_amdgcn_rcpf(bfhi(gb[j]));
;                         acc[ai][bj][m][1][2 * j] *= bflo(ga[2 + j]) * __builtin_amdgcn_rcpf(bflo(gb[2 + j])); acc[ai][bj][m][1][2 * j + 1] *= bfhi(ga[2 + j]) * __builtin_amdgcn_rcpf(bfhi(gb[2 + j])); } }
;                 asm volatile("" ::: "memory"); }
.LBB0_78:
	s_cmpk_lg_i32 s60, 0x800
	s_cbranch_scc1 .LBB0_77
	v_mul_u32_u24_e32 v161, 0x6200, v160
	v_lshl_add_u32 v161, v162, 1, v161
	s_add_u32 s62, s40, 0x4a00
	s_addc_u32 s63, s41, 0
	global_load_dwordx4 v[130:133], v161, s[62:63] offset:-2048
	global_load_dwordx4 v[134:137], v161, s[62:63] offset:2048
	s_add_u32 s62, s40, 0x4b00
	s_addc_u32 s63, s41, 0
	global_load_dwordx4 v[186:189], v161, s[62:63] offset:-2048
	global_load_dwordx4 v[190:193], v161, s[62:63] offset:2048
	s_add_u32 s62, s40, 0x66a00
	s_addc_u32 s63, s41, 0
	global_load_dwordx4 v[194:197], v161, s[62:63] offset:-2048
	global_load_dwordx4 v[198:201], v161, s[62:63] offset:2048
	s_add_u32 s62, s40, 0x66b00
	s_addc_u32 s63, s41, 0
	global_load_dwordx4 v[202:205], v161, s[62:63] offset:-2048
	global_load_dwordx4 v[206:209], v161, s[62:63] offset:2048
	s_add_u32 s62, s40, 0xc8a00
	s_addc_u32 s63, s41, 0
	global_load_dwordx4 v[214:217], v161, s[62:63] offset:-2048
	global_load_dwordx4 v[218:221], v161, s[62:63] offset:2048
	s_add_u32 s62, s40, 0xc8b00
	s_addc_u32 s63, s41, 0
	global_load_dwordx4 v[222:225], v161, s[62:63] offset:-2048
	global_load_dwordx4 v[226:229], v161, s[62:63] offset:2048
	s_add_u32 s62, s40, 0x12aa00
	s_addc_u32 s63, s41, 0
	global_load_dwordx4 v[230:233], v161, s[62:63] offset:-2048
	global_load_dwordx4 v[234:237], v161, s[62:63] offset:2048
	s_add_u32 s62, s40, 0x12ab00
	s_addc_u32 s63, s41, 0
	global_load_dwordx4 v[238:241], v161, s[62:63] offset:-2048
	global_load_dwordx4 v[242:245], v161, s[62:63] offset:2048
	s_waitcnt vmcnt(14)
	v_lshlrev_b32_e32 v144, 16, v134
	v_and_b32_e32 v145, 0xffff0000, v134
	v_lshlrev_b32_e32 v168, 16, v135
	v_and_b32_e32 v169, 0xffff0000, v135
	v_rcp_f32_e32 v144, v144
	v_rcp_f32_e32 v145, v145
	v_rcp_f32_e32 v168, v168
	v_rcp_f32_e32 v169, v169
	v_lshlrev_b32_e32 v142, 16, v130
	v_and_b32_e32 v143, 0xffff0000, v130
	v_pk_mul_f32 v[144:145], v[144:145], v[142:143]
	v_lshlrev_b32_e32 v142, 16, v131
	v_and_b32_e32 v143, 0xffff0000, v131
	v_pk_mul_f32 v[168:169], v[168:169], v[142:143]
	v_pk_mul_f32 v[126:127], v[126:127], v[144:145]
	v_pk_mul_f32 v[128:129], v[128:129], v[168:169]
	v_lshlrev_b32_e32 v144, 16, v136
	v_and_b32_e32 v145, 0xffff0000, v136
	v_lshlrev_b32_e32 v168, 16, v137
	v_and_b32_e32 v169, 0xffff0000, v137
	v_rcp_f32_e32 v144, v144
	v_rcp_f32_e32 v145, v145
	v_rcp_f32_e32 v168, v168
	v_rcp_f32_e32 v169, v169
	v_lshlrev_b32_e32 v142, 16, v132
	v_and_b32_e32 v143, 0xffff0000, v132
	v_pk_mul_f32 v[144:145], v[144:145], v[142:143]
	v_lshlrev_b32_e32 v142, 16, v133
	v_and_b32_e32 v143, 0xffff0000, v133
	v_pk_mul_f32 v[168:169], v[168:169], v[142:143]
	v_pk_mul_f32 v[122:123], v[122:123], v[144:145]
	v_pk_mul_f32 v[124:125], v[124:125], v[168:169]
	s_add_u32 s62, s40, 0x314a00
	s_addc_u32 s63, s41, 0
	global_load_dwordx4 v[130:133], v161, s[62:63] offset:-2048
	global_load_dwordx4 v[134:137], v161, s[62:63] offset:2048
	s_waitcnt vmcnt(14)
	v_lshlrev_b32_e32 v144, 16, v190
	v_and_b32_e32 v145, 0xffff0000, v190
	v_lshlrev_b32_e32 v168, 16, v191
	v_and_b32_e32 v169, 0xffff0000, v191
	v_rcp_f32_e32 v144, v144
	v_rcp_f32_e32 v145, v145
	v_rcp_f32_e32 v168, v168
	v_rcp_f32_e32 v169, v169
	v_lshlrev_b32_e32 v142, 16, v186
	v_and_b32_e32 v143, 0xffff0000, v186
	v_pk_mul_f32 v[144:145], v[144:145], v[142:143]
	v_lshlrev_b32_e32 v142, 16, v187
	v_and_b32_e32 v143, 0xffff0000, v187
	v_pk_mul_f32 v[168:169], v[168:169], v[142:143]
	v_pk_mul_f32 v[118:119], v[118:119], v[144:145]
	v_pk_mul_f32 v[120:121], v[120:121], v[168:169]
	v_lshlrev_b32_e32 v144, 16, v192
	v_and_b32_e32 v145, 0xffff0000, v192
	v_lshlrev_b32_e32 v168, 16, v193
	v_and_b32_e32 v169, 0xffff0000, v193
	v_rcp_f32_e32 v144, v144
	v_rcp_f32_e32 v145, v145
	v_rcp_f32_e32 v168, v168
	v_rcp_f32_e32 v169, v169
	v_lshlrev_b32_e32 v142, 16, v188
	v_and_b32_e32 v143, 0xffff0000, v188
	v_pk_mul_f32 v[144:145], v[144:145], v[142:143]
	v_lshlrev_b32_e32 v142, 16, v189
	v_and_b32_e32 v143, 0xffff0000, v189
	v_pk_mul_f32 v[168:169], v[168:169], v[142:143]
	v_pk_mul_f32 v[114:115], v[114:115], v[144:145]
	v_pk_mul_f32 v[116:117], v[116:117], v[168:169]
	s_add_u32 s62, s40, 0x314b00
	s_addc_u32 s63, s41, 0
	global_load_dwordx4 v[186:189], v161, s[62:63] offset:-2048
	global_load_dwordx4 v[190:193], v161, s[62:63] offset:2048
	s_waitcnt vmcnt(14)
	v_lshlrev_b32_e32 v144, 16, v198
	v_and_b32_e32 v145, 0xffff0000, v198
	v_lshlrev_b32_e32 v168, 16, v199
	v_and_b32_e32 v169, 0xffff0000, v199
	v_rcp_f32_e32 v144, v144
	v_rcp_f32_e32 v145, v145
	v_rcp_f32_e32 v168, v168
	v_rcp_f32_e32 v169, v169
	v_lshlrev_b32_e32 v142, 16, v194
	v_and_b32_e32 v143, 0xffff0000, v194
	v_pk_mul_f32 v[144:145], v[144:145], v[142:143]
	v_lshlrev_b32_e32 v142, 16, v195
	v_and_b32_e32 v143, 0xffff0000, v195
	v_pk_mul_f32 v[168:169], v[168:169], v[142:143]
	v_pk_mul_f32 v[110:111], v[110:111], v[144:145]
	v_pk_mul_f32 v[112:113], v[112:113], v[168:169]
	v_lshlrev_b32_e32 v144, 16, v200
	v_and_b32_e32 v145, 0xffff0000, v200
	v_lshlrev_b32_e32 v168, 16, v201
	v_and_b32_e32 v169, 0xffff0000, v201
	v_rcp_f32_e32 v144, v144
	v_rcp_f32_e32 v145, v145
	v_rcp_f32_e32 v168, v168
	v_rcp_f32_e32 v169, v169
	v_lshlrev_b32_e32 v142, 16, v196
	v_and_b32_e32 v143, 0xffff0000, v196
	v_pk_mul_f32 v[144:145], v[144:145], v[142:143]
	v_lshlrev_b32_e32 v142, 16, v197
	v_and_b32_e32 v143, 0xffff0000, v197
	v_pk_mul_f32 v[168:169], v[168:169], v[142:143]
	v_pk_mul_f32 v[106:107], v[106:107], v[144:145]
	v_pk_mul_f32 v[108:109], v[108:109], v[168:169]
	s_add_u32 s62, s40, 0x376a00
	s_addc_u32 s63, s41, 0
	global_load_dwordx4 v[194:197], v161, s[62:63] offset:-2048
	global_load_dwordx4 v[198:201], v161, s[62:63] offset:2048
	s_waitcnt vmcnt(14)
; __device__ __forceinline__ float bflo(unsigned w) { return __uint_as_float(w << 16); }
; __device__ __forceinline__ float bfhi(unsigned w) { return __uint_as_float(w & 0xffff0000u); }
;     __device__ __forceinline__ void mid(f32x4 (&acc)[2][2][4][2], const Unit& u, int wr, int wc, int fr, int fq) const {
;     ...
;             for (int m = 0; m < 4; ++m) { const size_t row = (size_t)(row0 + ai * HALF + m * 16);
; #pragma unroll
;                 for (int bj = 0; bj < 2; ++bj) { const int col = col0 + bj * HALF;
;                     const u32x4 ga = *(const u32x4*)(P + row * LDP + PC_GA + col), gb = *(const u32x4*)(P + row * LDP + PC_GB + col);
; #pragma unroll
;                     for (int j = 0; j < 2; ++j) {
;                         acc[ai][bj][m][0][2 * j] *= bflo(ga[j]) * __builtin_amdgcn_rcpf(bflo(gb[j])); acc[ai][bj][m][0][2 * j + 1] *= bfhi(ga[j]) * __builtin_amdgcn_rcpf(bfhi(gb[j]));
;                         acc[ai][bj][m][1][2 * j] *= bflo(ga[2 + j]) * __builtin_amdgcn_rcpf(bflo(gb[2 + j])); acc[ai][bj][m][1][2 * j + 1] *= bfhi(ga[2 + j]) * __builtin_amdgcn_rcpf(bfhi(gb[2 + j])); } }
	v_lshlrev_b32_e32 v144, 16, v206
	v_and_b32_e32 v145, 0xffff0000, v206
	v_lshlrev_b32_e32 v168, 16, v207
	v_and_b32_e32 v169, 0xffff0000, v207
	v_rcp_f32_e32 v144, v144
	v_rcp_f32_e32 v145, v145
	v_rcp_f32_e32 v168, v168
	v_rcp_f32_e32 v169, v169
	v_lshlrev_b32_e32 v142, 16, v202
	v_and_b32_e32 v143, 0xffff0000, v202
	v_pk_mul_f32 v[144:145], v[144:145], v[142:143]
	v_lshlrev_b32_e32 v142, 16, v203
	v_and_b32_e32 v143, 0xffff0000, v203
	v_pk_mul_f32 v[168:169], v[168:169], v[142:143]
	v_pk_mul_f32 v[102:103], v[102:103], v[144:145]
	v_pk_mul_f32 v[104:105], v[104:105], v[168:169]
	v_lshlrev_b32_e32 v144, 16, v208
	v_and_b32_e32 v145, 0xffff0000, v208
	v_lshlrev_b32_e32 v168, 16, v209
	v_and_b32_e32 v169, 0xffff0000, v209
	v_rcp_f32_e32 v144, v144
	v_rcp_f32_e32 v145, v145
	v_rcp_f32_e32 v168, v168
	v_rcp_f32_e32 v169, v169
	v_lshlrev_b32_e32 v142, 16, v204
	v_and_b32_e32 v143, 0xffff0000, v204
	v_pk_mul_f32 v[144:145], v[144:145], v[142:143]
	v_lshlrev_b32_e32 v142, 16, v205
	v_and_b32_e32 v143, 0xffff0000, v205
	v_pk_mul_f32 v[168:169], v[168:169], v[142:143]
	v_pk_mul_f32 v[98:99], v[98:99], v[144:145]
	v_pk_mul_f32 v[100:101], v[100:101], v[168:169]
	s_add_u32 s62, s40, 0x376b00
	s_addc_u32 s63, s41, 0
	global_load_dwordx4 v[202:205], v161, s[62:63] offset:-2048
	global_load_dwordx4 v[206:209], v161, s[62:63] offset:2048
	s_waitcnt vmcnt(14)
	v_lshlrev_b32_e32 v144, 16, v218
	v_and_b32_e32 v145, 0xffff0000, v218
	v_lshlrev_b32_e32 v168, 16, v219
	v_and_b32_e32 v169, 0xffff0000, v219
	v_rcp_f32_e32 v144, v144
	v_rcp_f32_e32 v145, v145
	v_rcp_f32_e32 v168, v168
	v_rcp_f32_e32 v169, v169
	v_lshlrev_b32_e32 v142, 16, v214
	v_and_b32_e32 v143, 0xffff0000, v214
	v_pk_mul_f32 v[144:145], v[144:145], v[142:143]
	v_lshlrev_b32_e32 v142, 16, v215
	v_and_b32_e32 v143, 0xffff0000, v215
	v_pk_mul_f32 v[168:169], v[168:169], v[142:143]
	v_pk_mul_f32 v[94:95], v[94:95], v[144:145]
	v_pk_mul_f32 v[96:97], v[96:97], v[168:169]
	v_lshlrev_b32_e32 v144, 16, v220
	v_and_b32_e32 v145, 0xffff0000, v220
	v_lshlrev_b32_e32 v168, 16, v221
	v_and_b32_e32 v169, 0xffff0000, v221
	v_rcp_f32_e32 v144, v144
	v_rcp_f32_e32 v145, v145
	v_rcp_f32_e32 v168, v168
	v_rcp_f32_e32 v169, v169
	v_lshlrev_b32_e32 v142, 16, v216
	v_and_b32_e32 v143, 0xffff0000, v216
	v_pk_mul_f32 v[144:145], v[144:145], v[142:143]
	v_lshlrev_b32_e32 v142, 16, v217
	v_and_b32_e32 v143, 0xffff0000, v217
	v_pk_mul_f32 v[168:169], v[168:169], v[142:143]
	v_pk_mul_f32 v[90:91], v[90:91], v[144:145]
	v_pk_mul_f32 v[92:93], v[92:93], v[168:169]
	s_add_u32 s62, s40, 0x3d8a00
	s_addc_u32 s63, s41, 0
	global_load_dwordx4 v[214:217], v161, s[62:63] offset:-2048
	global_load_dwordx4 v[218:221], v161, s[62:63] offset:2048
	s_waitcnt vmcnt(14)
	v_lshlrev_b32_e32 v144, 16, v226
	v_and_b32_e32 v145, 0xffff0000, v226
	v_lshlrev_b32_e32 v168, 16, v227
	v_and_b32_e32 v169, 0xffff0000, v227
	v_rcp_f32_e32 v144, v144
	v_rcp_f32_e32 v145, v145
	v_rcp_f32_e32 v168, v168
	v_rcp_f32_e32 v169, v169
	v_lshlrev_b32_e32 v142, 16, v222
	v_and_b32_e32 v143, 0xffff0000, v222
	v_pk_mul_f32 v[144:145], v[144:145], v[142:143]
	v_lshlrev_b32_e32 v142, 16, v223
	v_and_b32_e32 v143, 0xffff0000, v223
	v_pk_mul_f32 v[168:169], v[168:169], v[142:143]
	v_pk_mul_f32 v[86:87], v[86:87], v[144:145]
	v_pk_mul_f32 v[88:89], v[88:89], v[168:169]
	v_lshlrev_b32_e32 v144, 16, v228
	v_and_b32_e32 v145, 0xffff0000, v228
	v_lshlrev_b32_e32 v168, 16, v229
	v_and_b32_e32 v169, 0xffff0000, v229
	v_rcp_f32_e32 v144, v144
	v_rcp_f32_e32 v145, v145
	v_rcp_f32_e32 v168, v168
	v_rcp_f32_e32 v169, v169
	v_lshlrev_b32_e32 v142, 16, v224
	v_and_b32_e32 v143, 0xffff0000, v224
	v_pk_mul_f32 v[144:145], v[144:145], v[142:143]
	v_lshlrev_b32_e32 v142, 16, v225
	v_and_b32_e32 v143, 0xffff0000, v225
	v_pk_mul_f32 v[168:169], v[168:169], v[142:143]
	v_pk_mul_f32 v[82:83], v[82:83], v[144:145]
	v_pk_mul_f32 v[84:85], v[84:85], v[168:169]
	s_add_u32 s62, s40, 0x3d8b00
	s_addc_u32 s63, s41, 0
	global_load_dwordx4 v[222:225], v161, s[62:63] offset:-2048
	global_load_dwordx4 v[226:229], v161, s[62:63] offset:2048
	s_waitcnt vmcnt(14)
	v_lshlrev_b32_e32 v144, 16, v234
	v_and_b32_e32 v145, 0xffff0000, v234
	v_lshlrev_b32_e32 v168, 16, v235
	v_and_b32_e32 v169, 0xffff0000, v235
	v_rcp_f32_e32 v144, v144
	v_rcp_f32_e32 v145, v145
	v_rcp_f32_e32 v168, v168
	v_rcp_f32_e32 v169, v169
	v_lshlrev_b32_e32 v142, 16, v230
	v_and_b32_e32 v143, 0xffff0000, v230
	v_pk_mul_f32 v[144:145], v[144:145], v[142:143]
	v_lshlrev_b32_e32 v142, 16, v231
	v_and_b32_e32 v143, 0xffff0000, v231
	v_pk_mul_f32 v[168:169], v[168:169], v[142:143]
	v_pk_mul_f32 v[78:79], v[78:79], v[144:145]
	v_pk_mul_f32 v[80:81], v[80:81], v[168:169]
	v_lshlrev_b32_e32 v144, 16, v236
	v_and_b32_e32 v145, 0xffff0000, v236
	v_lshlrev_b32_e32 v168, 16, v237
	v_and_b32_e32 v169, 0xffff0000, v237
	v_rcp_f32_e32 v144, v144
	v_rcp_f32_e32 v145, v145
	v_rcp_f32_e32 v168, v168
	v_rcp_f32_e32 v169, v169
	v_lshlrev_b32_e32 v142, 16, v232
	v_and_b32_e32 v143, 0xffff0000, v232
	v_pk_mul_f32 v[144:145], v[144:145], v[142:143]
	v_lshlrev_b32_e32 v142, 16, v233
	v_and_b32_e32 v143, 0xffff0000, v233
	v_pk_mul_f32 v[168:169], v[168:169], v[142:143]
	v_pk_mul_f32 v[74:75], v[74:75], v[144:145]
	v_pk_mul_f32 v[76:77], v[76:77], v[168:169]
	s_add_u32 s62, s40, 0x43aa00
	s_addc_u32 s63, s41, 0
	global_load_dwordx4 v[230:233], v161, s[62:63] offset:-2048
	global_load_dwordx4 v[234:237], v161, s[62:63] offset:2048
	s_waitcnt vmcnt(14)
; __device__ __forceinline__ float bflo(unsigned w) { return __uint_as_float(w << 16); }
; __device__ __forceinline__ float bfhi(unsigned w) { return __uint_as_float(w & 0xffff0000u); }
;     __device__ __forceinline__ void mid(f32x4 (&acc)[2][2][4][2], const Unit& u, int wr, int wc, int fr, int fq) const {
;     ...
;             for (int m = 0; m < 4; ++m) { const size_t row = (size_t)(row0 + ai * HALF + m * 16);
; #pragma unroll
;                 for (int bj = 0; bj < 2; ++bj) { const int col = col0 + bj * HALF;
;                     const u32x4 ga = *(const u32x4*)(P + row * LDP + PC_GA + col), gb = *(const u32x4*)(P + row * LDP + PC_GB + col);
; #pragma unroll
;                     for (int j = 0; j < 2; ++j) {
;                         acc[ai][bj][m][0][2 * j] *= bflo(ga[j]) * __builtin_amdgcn_rcpf(bflo(gb[j])); acc[ai][bj][m][0][2 * j + 1] *= bfhi(ga[j]) * __builtin_amdgcn_rcpf(bfhi(gb[j]));
;                         acc[ai][bj][m][1][2 * j] *= bflo(ga[2 + j]) * __builtin_amdgcn_rcpf(bflo(gb[2 + j])); acc[ai][bj][m][1][2 * j + 1] *= bfhi(ga[2 + j]) * __builtin_amdgcn_rcpf(bfhi(gb[2 + j])); } }
	v_lshlrev_b32_e32 v144, 16, v242
	v_and_b32_e32 v145, 0xffff0000, v242
	v_lshlrev_b32_e32 v168, 16, v243
	v_and_b32_e32 v169, 0xffff0000, v243
	v_rcp_f32_e32 v144, v144
	v_rcp_f32_e32 v145, v145
	v_rcp_f32_e32 v168, v168
	v_rcp_f32_e32 v169, v169
	v_lshlrev_b32_e32 v142, 16, v238
	v_and_b32_e32 v143, 0xffff0000, v238
	v_pk_mul_f32 v[144:145], v[144:145], v[142:143]
	v_lshlrev_b32_e32 v142, 16, v239
	v_and_b32_e32 v143, 0xffff0000, v239
	v_pk_mul_f32 v[168:169], v[168:169], v[142:143]
	v_pk_mul_f32 v[70:71], v[70:71], v[144:145]
	v_pk_mul_f32 v[72:73], v[72:73], v[168:169]
	v_lshlrev_b32_e32 v144, 16, v244
	v_and_b32_e32 v145, 0xffff0000, v244
	v_lshlrev_b32_e32 v168, 16, v245
	v_and_b32_e32 v169, 0xffff0000, v245
	v_rcp_f32_e32 v144, v144
	v_rcp_f32_e32 v145, v145
	v_rcp_f32_e32 v168, v168
	v_rcp_f32_e32 v169, v169
	v_lshlrev_b32_e32 v142, 16, v240
	v_and_b32_e32 v143, 0xffff0000, v240
	v_pk_mul_f32 v[144:145], v[144:145], v[142:143]
	v_lshlrev_b32_e32 v142, 16, v241
	v_and_b32_e32 v143, 0xffff0000, v241
	v_pk_mul_f32 v[168:169], v[168:169], v[142:143]
	v_pk_mul_f32 v[66:67], v[66:67], v[144:145]
	v_pk_mul_f32 v[68:69], v[68:69], v[168:169]
	s_add_u32 s62, s40, 0x43ab00
	s_addc_u32 s63, s41, 0
	global_load_dwordx4 v[238:241], v161, s[62:63] offset:-2048
	global_load_dwordx4 v[242:245], v161, s[62:63] offset:2048
	s_waitcnt vmcnt(14)
	v_lshlrev_b32_e32 v144, 16, v134
	v_and_b32_e32 v145, 0xffff0000, v134
	v_lshlrev_b32_e32 v168, 16, v135
	v_and_b32_e32 v169, 0xffff0000, v135
	v_rcp_f32_e32 v144, v144
	v_rcp_f32_e32 v145, v145
	v_rcp_f32_e32 v168, v168
	v_rcp_f32_e32 v169, v169
	v_lshlrev_b32_e32 v142, 16, v130
	v_and_b32_e32 v143, 0xffff0000, v130
	v_pk_mul_f32 v[144:145], v[144:145], v[142:143]
	v_lshlrev_b32_e32 v142, 16, v131
	v_and_b32_e32 v143, 0xffff0000, v131
	v_pk_mul_f32 v[168:169], v[168:169], v[142:143]
	v_pk_mul_f32 v[62:63], v[62:63], v[144:145]
	v_pk_mul_f32 v[64:65], v[64:65], v[168:169]
	v_lshlrev_b32_e32 v144, 16, v136
	v_and_b32_e32 v145, 0xffff0000, v136
	v_lshlrev_b32_e32 v168, 16, v137
	v_and_b32_e32 v169, 0xffff0000, v137
	v_rcp_f32_e32 v144, v144
	v_rcp_f32_e32 v145, v145
	v_rcp_f32_e32 v168, v168
	v_rcp_f32_e32 v169, v169
	v_lshlrev_b32_e32 v142, 16, v132
	v_and_b32_e32 v143, 0xffff0000, v132
	v_pk_mul_f32 v[144:145], v[144:145], v[142:143]
	v_lshlrev_b32_e32 v142, 16, v133
	v_and_b32_e32 v143, 0xffff0000, v133
	v_pk_mul_f32 v[168:169], v[168:169], v[142:143]
	v_pk_mul_f32 v[58:59], v[58:59], v[144:145]
	v_pk_mul_f32 v[60:61], v[60:61], v[168:169]
	s_waitcnt vmcnt(12)
	v_lshlrev_b32_e32 v144, 16, v190
	v_and_b32_e32 v145, 0xffff0000, v190
	v_lshlrev_b32_e32 v168, 16, v191
	v_and_b32_e32 v169, 0xffff0000, v191
	v_rcp_f32_e32 v144, v144
	v_rcp_f32_e32 v145, v145
	v_rcp_f32_e32 v168, v168
	v_rcp_f32_e32 v169, v169
	v_lshlrev_b32_e32 v142, 16, v186
	v_and_b32_e32 v143, 0xffff0000, v186
	v_pk_mul_f32 v[144:145], v[144:145], v[142:143]
	v_lshlrev_b32_e32 v142, 16, v187
	v_and_b32_e32 v143, 0xffff0000, v187
	v_pk_mul_f32 v[168:169], v[168:169], v[142:143]
	v_pk_mul_f32 v[54:55], v[54:55], v[144:145]
	v_pk_mul_f32 v[56:57], v[56:57], v[168:169]
	v_lshlrev_b32_e32 v144, 16, v192
	v_and_b32_e32 v145, 0xffff0000, v192
	v_lshlrev_b32_e32 v168, 16, v193
	v_and_b32_e32 v169, 0xffff0000, v193
	v_rcp_f32_e32 v144, v144
	v_rcp_f32_e32 v145, v145
	v_rcp_f32_e32 v168, v168
	v_rcp_f32_e32 v169, v169
	v_lshlrev_b32_e32 v142, 16, v188
	v_and_b32_e32 v143, 0xffff0000, v188
	v_pk_mul_f32 v[144:145], v[144:145], v[142:143]
	v_lshlrev_b32_e32 v142, 16, v189
	v_and_b32_e32 v143, 0xffff0000, v189
	v_pk_mul_f32 v[168:169], v[168:169], v[142:143]
	v_pk_mul_f32 v[50:51], v[50:51], v[144:145]
	v_pk_mul_f32 v[52:53], v[52:53], v[168:169]
	s_waitcnt vmcnt(10)
	v_lshlrev_b32_e32 v144, 16, v198
	v_and_b32_e32 v145, 0xffff0000, v198
	v_lshlrev_b32_e32 v168, 16, v199
	v_and_b32_e32 v169, 0xffff0000, v199
	v_rcp_f32_e32 v144, v144
	v_rcp_f32_e32 v145, v145
	v_rcp_f32_e32 v168, v168
	v_rcp_f32_e32 v169, v169
	v_lshlrev_b32_e32 v142, 16, v194
	v_and_b32_e32 v143, 0xffff0000, v194
	v_pk_mul_f32 v[144:145], v[144:145], v[142:143]
	v_lshlrev_b32_e32 v142, 16, v195
	v_and_b32_e32 v143, 0xffff0000, v195
	v_pk_mul_f32 v[168:169], v[168:169], v[142:143]
	v_pk_mul_f32 v[46:47], v[46:47], v[144:145]
	v_pk_mul_f32 v[48:49], v[48:49], v[168:169]
	v_lshlrev_b32_e32 v144, 16, v200
	v_and_b32_e32 v145, 0xffff0000, v200
	v_lshlrev_b32_e32 v168, 16, v201
	v_and_b32_e32 v169, 0xffff0000, v201
	v_rcp_f32_e32 v144, v144
	v_rcp_f32_e32 v145, v145
	v_rcp_f32_e32 v168, v168
	v_rcp_f32_e32 v169, v169
	v_lshlrev_b32_e32 v142, 16, v196
	v_and_b32_e32 v143, 0xffff0000, v196
	v_pk_mul_f32 v[144:145], v[144:145], v[142:143]
	v_lshlrev_b32_e32 v142, 16, v197
	v_and_b32_e32 v143, 0xffff0000, v197
	v_pk_mul_f32 v[168:169], v[168:169], v[142:143]
	v_pk_mul_f32 v[42:43], v[42:43], v[144:145]
	v_pk_mul_f32 v[44:45], v[44:45], v[168:169]
	s_waitcnt vmcnt(8)
; __device__ __forceinline__ float bflo(unsigned w) { return __uint_as_float(w << 16); }
; __device__ __forceinline__ float bfhi(unsigned w) { return __uint_as_float(w & 0xffff0000u); }
;     __device__ __forceinline__ void mid(f32x4 (&acc)[2][2][4][2], const Unit& u, int wr, int wc, int fr, int fq) const {
;     ...
;             for (int m = 0; m < 4; ++m) { const size_t row = (size_t)(row0 + ai * HALF + m * 16);
; #pragma unroll
;                 for (int bj = 0; bj < 2; ++bj) { const int col = col0 + bj * HALF;
;                     const u32x4 ga = *(const u32x4*)(P + row * LDP + PC_GA + col), gb = *(const u32x4*)(P + row * LDP + PC_GB + col);
; #pragma unroll
;                     for (int j = 0; j < 2; ++j) {
;                         acc[ai][bj][m][0][2 * j] *= bflo(ga[j]) * __builtin_amdgcn_rcpf(bflo(gb[j])); acc[ai][bj][m][0][2 * j + 1] *= bfhi(ga[j]) * __builtin_amdgcn_rcpf(bfhi(gb[j]));
;                         acc[ai][bj][m][1][2 * j] *= bflo(ga[2 + j]) * __builtin_amdgcn_rcpf(bflo(gb[2 + j])); acc[ai][bj][m][1][2 * j + 1] *= bfhi(ga[2 + j]) * __builtin_amdgcn_rcpf(bfhi(gb[2 + j])); } }
;                 asm volatile("" ::: "memory"); }
	v_lshlrev_b32_e32 v144, 16, v206
	v_and_b32_e32 v145, 0xffff0000, v206
	v_lshlrev_b32_e32 v168, 16, v207
	v_and_b32_e32 v169, 0xffff0000, v207
	v_rcp_f32_e32 v144, v144
	v_rcp_f32_e32 v145, v145
	v_rcp_f32_e32 v168, v168
	v_rcp_f32_e32 v169, v169
	v_lshlrev_b32_e32 v142, 16, v202
	v_and_b32_e32 v143, 0xffff0000, v202
	v_pk_mul_f32 v[144:145], v[144:145], v[142:143]
	v_lshlrev_b32_e32 v142, 16, v203
	v_and_b32_e32 v143, 0xffff0000, v203
	v_pk_mul_f32 v[168:169], v[168:169], v[142:143]
	v_pk_mul_f32 v[38:39], v[38:39], v[144:145]
	v_pk_mul_f32 v[40:41], v[40:41], v[168:169]
	v_lshlrev_b32_e32 v144, 16, v208
	v_and_b32_e32 v145, 0xffff0000, v208
	v_lshlrev_b32_e32 v168, 16, v209
	v_and_b32_e32 v169, 0xffff0000, v209
	v_rcp_f32_e32 v144, v144
	v_rcp_f32_e32 v145, v145
	v_rcp_f32_e32 v168, v168
	v_rcp_f32_e32 v169, v169
	v_lshlrev_b32_e32 v142, 16, v204
	v_and_b32_e32 v143, 0xffff0000, v204
	v_pk_mul_f32 v[144:145], v[144:145], v[142:143]
	v_lshlrev_b32_e32 v142, 16, v205
	v_and_b32_e32 v143, 0xffff0000, v205
	v_pk_mul_f32 v[168:169], v[168:169], v[142:143]
	v_pk_mul_f32 v[34:35], v[34:35], v[144:145]
	v_pk_mul_f32 v[36:37], v[36:37], v[168:169]
	s_waitcnt vmcnt(6)
	v_lshlrev_b32_e32 v144, 16, v218
	v_and_b32_e32 v145, 0xffff0000, v218
	v_lshlrev_b32_e32 v168, 16, v219
	v_and_b32_e32 v169, 0xffff0000, v219
	v_rcp_f32_e32 v144, v144
	v_rcp_f32_e32 v145, v145
	v_rcp_f32_e32 v168, v168
	v_rcp_f32_e32 v169, v169
	v_lshlrev_b32_e32 v142, 16, v214
	v_and_b32_e32 v143, 0xffff0000, v214
	v_pk_mul_f32 v[144:145], v[144:145], v[142:143]
	v_lshlrev_b32_e32 v142, 16, v215
	v_and_b32_e32 v143, 0xffff0000, v215
	v_pk_mul_f32 v[168:169], v[168:169], v[142:143]
	v_pk_mul_f32 v[30:31], v[30:31], v[144:145]
	v_pk_mul_f32 v[32:33], v[32:33], v[168:169]
	v_lshlrev_b32_e32 v144, 16, v220
	v_and_b32_e32 v145, 0xffff0000, v220
	v_lshlrev_b32_e32 v168, 16, v221
	v_and_b32_e32 v169, 0xffff0000, v221
	v_rcp_f32_e32 v144, v144
	v_rcp_f32_e32 v145, v145
	v_rcp_f32_e32 v168, v168
	v_rcp_f32_e32 v169, v169
	v_lshlrev_b32_e32 v142, 16, v216
	v_and_b32_e32 v143, 0xffff0000, v216
	v_pk_mul_f32 v[144:145], v[144:145], v[142:143]
	v_lshlrev_b32_e32 v142, 16, v217
	v_and_b32_e32 v143, 0xffff0000, v217
	v_pk_mul_f32 v[168:169], v[168:169], v[142:143]
	v_pk_mul_f32 v[26:27], v[26:27], v[144:145]
	v_pk_mul_f32 v[28:29], v[28:29], v[168:169]
	s_waitcnt vmcnt(4)
	v_lshlrev_b32_e32 v144, 16, v226
	v_and_b32_e32 v145, 0xffff0000, v226
	v_lshlrev_b32_e32 v168, 16, v227
	v_and_b32_e32 v169, 0xffff0000, v227
	v_rcp_f32_e32 v144, v144
	v_rcp_f32_e32 v145, v145
	v_rcp_f32_e32 v168, v168
	v_rcp_f32_e32 v169, v169
	v_lshlrev_b32_e32 v142, 16, v222
	v_and_b32_e32 v143, 0xffff0000, v222
	v_pk_mul_f32 v[144:145], v[144:145], v[142:143]
	v_lshlrev_b32_e32 v142, 16, v223
	v_and_b32_e32 v143, 0xffff0000, v223
	v_pk_mul_f32 v[168:169], v[168:169], v[142:143]
	v_pk_mul_f32 v[22:23], v[22:23], v[144:145]
	v_pk_mul_f32 v[24:25], v[24:25], v[168:169]
	v_lshlrev_b32_e32 v144, 16, v228
	v_and_b32_e32 v145, 0xffff0000, v228
	v_lshlrev_b32_e32 v168, 16, v229
	v_and_b32_e32 v169, 0xffff0000, v229
	v_rcp_f32_e32 v144, v144
	v_rcp_f32_e32 v145, v145
	v_rcp_f32_e32 v168, v168
	v_rcp_f32_e32 v169, v169
	v_lshlrev_b32_e32 v142, 16, v224
	v_and_b32_e32 v143, 0xffff0000, v224
	v_pk_mul_f32 v[144:145], v[144:145], v[142:143]
	v_lshlrev_b32_e32 v142, 16, v225
	v_and_b32_e32 v143, 0xffff0000, v225
	v_pk_mul_f32 v[168:169], v[168:169], v[142:143]
	v_pk_mul_f32 v[18:19], v[18:19], v[144:145]
	v_pk_mul_f32 v[20:21], v[20:21], v[168:169]
	s_waitcnt vmcnt(2)
	v_lshlrev_b32_e32 v144, 16, v234
	v_and_b32_e32 v145, 0xffff0000, v234
	v_lshlrev_b32_e32 v168, 16, v235
	v_and_b32_e32 v169, 0xffff0000, v235
	v_rcp_f32_e32 v144, v144
	v_rcp_f32_e32 v145, v145
	v_rcp_f32_e32 v168, v168
	v_rcp_f32_e32 v169, v169
	v_lshlrev_b32_e32 v142, 16, v230
	v_and_b32_e32 v143, 0xffff0000, v230
	v_pk_mul_f32 v[144:145], v[144:145], v[142:143]
	v_lshlrev_b32_e32 v142, 16, v231
	v_and_b32_e32 v143, 0xffff0000, v231
	v_pk_mul_f32 v[168:169], v[168:169], v[142:143]
	v_pk_mul_f32 v[14:15], v[14:15], v[144:145]
	v_pk_mul_f32 v[16:17], v[16:17], v[168:169]
	v_lshlrev_b32_e32 v144, 16, v236
	v_and_b32_e32 v145, 0xffff0000, v236
	v_lshlrev_b32_e32 v168, 16, v237
	v_and_b32_e32 v169, 0xffff0000, v237
	v_rcp_f32_e32 v144, v144
	v_rcp_f32_e32 v145, v145
	v_rcp_f32_e32 v168, v168
	v_rcp_f32_e32 v169, v169
	v_lshlrev_b32_e32 v142, 16, v232
	v_and_b32_e32 v143, 0xffff0000, v232
	v_pk_mul_f32 v[144:145], v[144:145], v[142:143]
	v_lshlrev_b32_e32 v142, 16, v233
	v_and_b32_e32 v143, 0xffff0000, v233
	v_pk_mul_f32 v[168:169], v[168:169], v[142:143]
	v_pk_mul_f32 v[10:11], v[10:11], v[144:145]
	v_pk_mul_f32 v[12:13], v[12:13], v[168:169]
	s_waitcnt vmcnt(0)
	v_lshlrev_b32_e32 v144, 16, v242
	v_and_b32_e32 v145, 0xffff0000, v242
	v_lshlrev_b32_e32 v168, 16, v243
	v_and_b32_e32 v169, 0xffff0000, v243
	v_rcp_f32_e32 v144, v144
	v_rcp_f32_e32 v145, v145
	v_rcp_f32_e32 v168, v168
	v_rcp_f32_e32 v169, v169
	v_lshlrev_b32_e32 v142, 16, v238
	v_and_b32_e32 v143, 0xffff0000, v238
	v_pk_mul_f32 v[144:145], v[144:145], v[142:143]
	v_lshlrev_b32_e32 v142, 16, v239
	v_and_b32_e32 v143, 0xffff0000, v239
	v_pk_mul_f32 v[168:169], v[168:169], v[142:143]
	v_pk_mul_f32 v[6:7], v[6:7], v[144:145]
	v_pk_mul_f32 v[8:9], v[8:9], v[168:169]
	v_lshlrev_b32_e32 v144, 16, v244
	v_and_b32_e32 v145, 0xffff0000, v244
	v_lshlrev_b32_e32 v168, 16, v245
	v_and_b32_e32 v169, 0xffff0000, v245
	v_rcp_f32_e32 v144, v144
	v_rcp_f32_e32 v145, v145
	v_rcp_f32_e32 v168, v168
	v_rcp_f32_e32 v169, v169
	v_lshlrev_b32_e32 v142, 16, v240
	v_and_b32_e32 v143, 0xffff0000, v240
	v_pk_mul_f32 v[144:145], v[144:145], v[142:143]
	v_lshlrev_b32_e32 v142, 16, v241
	v_and_b32_e32 v143, 0xffff0000, v241
	v_pk_mul_f32 v[168:169], v[168:169], v[142:143]
	v_pk_mul_f32 v[2:3], v[2:3], v[144:145]
	v_pk_mul_f32 v[4:5], v[4:5], v[168:169]
	s_branch .LBB0_77

; __device__ __forceinline__ unsigned cvt_pk_bf16(float lo, float hi) { unsigned r; asm volatile("v_cvt_pk_bf16_f32 %0, %1, %2" : "=v"(r) : "v"(lo), "v"(hi)); return r; }
; __device__ __forceinline__ float bflo(unsigned w) { return __uint_as_float(w << 16); }
; __device__ __forceinline__ float bfhi(unsigned w) { return __uint_as_float(w & 0xffff0000u); }
;     __device__ __forceinline__ void operator()(const f32x4 (&acc)[2][2][4][2], const Unit& u, int wr, int wc, int fr, int fq) const {
;         const int row0 = u.pm * BM + wr * 64 + fr, col0 = u.pn * BM + wc * 32 + 8 * fq;
; #pragma unroll
;         for (int ai = 0; ai < 2; ++ai)
; #pragma unroll
;             for (int m = 0; m < 4; ++m) { const size_t row = (size_t)(row0 + ai * HALF + m * 16);
; #pragma unroll
;                 for (int bj = 0; bj < 2; ++bj) { const int col = col0 + bj * HALF;
;                     const u32x4 g = *(const u32x4*)(P + row * LDP + PC_GB + col);
;                     f32x4 v0 = acc[ai][bj][m][0], v1 = acc[ai][bj][m][1];
;                     v0[0] *= bflo(g.x); v0[1] *= bfhi(g.x); v0[2] *= bflo(g.y); v0[3] *= bfhi(g.y);
;                     v1[0] *= bflo(g.z); v1[1] *= bfhi(g.z); v1[2] *= bflo(g.w); v1[3] *= bfhi(g.w);
;                     u32x4 w; w.x = cvt_pk_bf16(v0[0], v0[1]); w.y = cvt_pk_bf16(v0[2], v0[3]); w.z = cvt_pk_bf16(v1[0], v1[1]); w.w = cvt_pk_bf16(v1[2], v1[3]);
.LBB0_82:
	v_mul_u32_u24_e32 v161, 0x6200, v160
	v_lshlrev_b32_e32 v163, 12, v160
	v_lshl_add_u32 v161, v162, 1, v161
	v_lshl_add_u32 v163, v162, 1, v163
	s_add_u32 s2, s40, 0x5200
	s_addc_u32 s3, s41, 0
	global_load_dwordx4 v[130:133], v161, s[2:3]
	s_add_u32 s2, s40, 0x5300
	s_addc_u32 s3, s41, 0
	global_load_dwordx4 v[134:137], v161, s[2:3]
	s_add_u32 s2, s40, 0x67200
	s_addc_u32 s3, s41, 0
	global_load_dwordx4 v[186:189], v161, s[2:3]
	s_add_u32 s2, s40, 0x67300
	s_addc_u32 s3, s41, 0
	global_load_dwordx4 v[190:193], v161, s[2:3]
	s_add_u32 s2, s40, 0xc9200
	s_addc_u32 s3, s41, 0
	global_load_dwordx4 v[194:197], v161, s[2:3]
	s_add_u32 s2, s40, 0xc9300
	s_addc_u32 s3, s41, 0
	global_load_dwordx4 v[198:201], v161, s[2:3]
	s_add_u32 s2, s40, 0x12b200
	s_addc_u32 s3, s41, 0
	global_load_dwordx4 v[202:205], v161, s[2:3]
	s_add_u32 s2, s40, 0x12b300
	s_addc_u32 s3, s41, 0
	global_load_dwordx4 v[206:209], v161, s[2:3]
	s_add_u32 s2, s40, 0x315200
	s_addc_u32 s3, s41, 0
	global_load_dwordx4 v[214:217], v161, s[2:3]
	s_add_u32 s2, s40, 0x315300
	s_addc_u32 s3, s41, 0
	global_load_dwordx4 v[218:221], v161, s[2:3]
	s_add_u32 s2, s40, 0x377200
	s_addc_u32 s3, s41, 0
	global_load_dwordx4 v[222:225], v161, s[2:3]
	s_add_u32 s2, s40, 0x377300
	s_addc_u32 s3, s41, 0
	global_load_dwordx4 v[226:229], v161, s[2:3]
	s_add_u32 s2, s40, 0x3d9200
	s_addc_u32 s3, s41, 0
	global_load_dwordx4 v[230:233], v161, s[2:3]
	s_add_u32 s2, s40, 0x3d9300
	s_addc_u32 s3, s41, 0
	global_load_dwordx4 v[234:237], v161, s[2:3]
	s_add_u32 s2, s40, 0x43b200
	s_addc_u32 s3, s41, 0
	global_load_dwordx4 v[238:241], v161, s[2:3]
	s_add_u32 s2, s40, 0x43b300
	s_addc_u32 s3, s41, 0
	global_load_dwordx4 v[242:245], v161, s[2:3]
	s_waitcnt vmcnt(15)
	v_lshlrev_b32_e32 v142, 16, v130
	v_and_b32_e32 v130, 0xffff0000, v130
	v_lshlrev_b32_e32 v143, 16, v131
	v_and_b32_e32 v131, 0xffff0000, v131
	v_lshlrev_b32_e32 v144, 16, v132
	v_and_b32_e32 v132, 0xffff0000, v132
	v_lshlrev_b32_e32 v145, 16, v133
	v_and_b32_e32 v133, 0xffff0000, v133
	v_mul_f32_e32 v126, v126, v142
	v_mul_f32_e32 v127, v127, v130
	v_mul_f32_e32 v128, v128, v143
	v_mul_f32_e32 v129, v129, v131
	v_mul_f32_e32 v122, v122, v144
	v_mul_f32_e32 v123, v123, v132
	v_mul_f32_e32 v124, v124, v145
	v_mul_f32_e32 v125, v125, v133
	v_cvt_pk_bf16_f32 v130, v126, v127
	v_cvt_pk_bf16_f32 v131, v128, v129
	v_cvt_pk_bf16_f32 v132, v122, v123
	v_cvt_pk_bf16_f32 v133, v124, v125
	s_waitcnt vmcnt(14)
	v_lshlrev_b32_e32 v142, 16, v134
	v_and_b32_e32 v134, 0xffff0000, v134
	v_lshlrev_b32_e32 v143, 16, v135
	v_and_b32_e32 v135, 0xffff0000, v135
	v_lshlrev_b32_e32 v144, 16, v136
	v_and_b32_e32 v136, 0xffff0000, v136
	v_lshlrev_b32_e32 v145, 16, v137
	v_and_b32_e32 v137, 0xffff0000, v137
	v_mul_f32_e32 v118, v118, v142
	v_mul_f32_e32 v119, v119, v134
	v_mul_f32_e32 v120, v120, v143
	v_mul_f32_e32 v121, v121, v135
	v_mul_f32_e32 v114, v114, v144
	v_mul_f32_e32 v115, v115, v136
	v_mul_f32_e32 v116, v116, v145
	v_mul_f32_e32 v117, v117, v137
	v_cvt_pk_bf16_f32 v134, v118, v119
	v_cvt_pk_bf16_f32 v135, v120, v121
	v_cvt_pk_bf16_f32 v136, v114, v115
	v_cvt_pk_bf16_f32 v137, v116, v117
	s_waitcnt vmcnt(13)
	v_lshlrev_b32_e32 v142, 16, v186
	v_and_b32_e32 v186, 0xffff0000, v186
	v_lshlrev_b32_e32 v143, 16, v187
	v_and_b32_e32 v187, 0xffff0000, v187
	v_lshlrev_b32_e32 v144, 16, v188
	v_and_b32_e32 v188, 0xffff0000, v188
	v_lshlrev_b32_e32 v145, 16, v189
	v_and_b32_e32 v189, 0xffff0000, v189
	v_mul_f32_e32 v110, v110, v142
	v_mul_f32_e32 v111, v111, v186
	v_mul_f32_e32 v112, v112, v143
	v_mul_f32_e32 v113, v113, v187
	v_mul_f32_e32 v106, v106, v144
	v_mul_f32_e32 v107, v107, v188
	v_mul_f32_e32 v108, v108, v145
	v_mul_f32_e32 v109, v109, v189
	v_cvt_pk_bf16_f32 v186, v110, v111
	v_cvt_pk_bf16_f32 v187, v112, v113
	v_cvt_pk_bf16_f32 v188, v106, v107
	v_cvt_pk_bf16_f32 v189, v108, v109
	s_waitcnt vmcnt(12)
	v_lshlrev_b32_e32 v142, 16, v190
	v_and_b32_e32 v190, 0xffff0000, v190
	v_lshlrev_b32_e32 v143, 16, v191
	v_and_b32_e32 v191, 0xffff0000, v191
	v_lshlrev_b32_e32 v144, 16, v192
	v_and_b32_e32 v192, 0xffff0000, v192
	v_lshlrev_b32_e32 v145, 16, v193
	v_and_b32_e32 v193, 0xffff0000, v193
	v_mul_f32_e32 v102, v102, v142
	v_mul_f32_e32 v103, v103, v190
	v_mul_f32_e32 v104, v104, v143
	v_mul_f32_e32 v105, v105, v191
	v_mul_f32_e32 v98, v98, v144
	v_mul_f32_e32 v99, v99, v192
	v_mul_f32_e32 v100, v100, v145
	v_mul_f32_e32 v101, v101, v193
	v_cvt_pk_bf16_f32 v190, v102, v103
	v_cvt_pk_bf16_f32 v191, v104, v105
	v_cvt_pk_bf16_f32 v192, v98, v99
	v_cvt_pk_bf16_f32 v193, v100, v101
	s_waitcnt vmcnt(11)
	v_lshlrev_b32_e32 v142, 16, v194
	v_and_b32_e32 v194, 0xffff0000, v194
	v_lshlrev_b32_e32 v143, 16, v195
	v_and_b32_e32 v195, 0xffff0000, v195
	v_lshlrev_b32_e32 v144, 16, v196
	v_and_b32_e32 v196, 0xffff0000, v196
	v_lshlrev_b32_e32 v145, 16, v197
	v_and_b32_e32 v197, 0xffff0000, v197
	v_mul_f32_e32 v94, v94, v142
	v_mul_f32_e32 v95, v95, v194
	v_mul_f32_e32 v96, v96, v143
	v_mul_f32_e32 v97, v97, v195
	v_mul_f32_e32 v90, v90, v144
	v_mul_f32_e32 v91, v91, v196
	v_mul_f32_e32 v92, v92, v145
	v_mul_f32_e32 v93, v93, v197
	v_cvt_pk_bf16_f32 v194, v94, v95
	v_cvt_pk_bf16_f32 v195, v96, v97
	v_cvt_pk_bf16_f32 v196, v90, v91
	v_cvt_pk_bf16_f32 v197, v92, v93
	s_waitcnt vmcnt(10)
	v_lshlrev_b32_e32 v142, 16, v198
	v_and_b32_e32 v198, 0xffff0000, v198
	v_lshlrev_b32_e32 v143, 16, v199
	v_and_b32_e32 v199, 0xffff0000, v199
	v_lshlrev_b32_e32 v144, 16, v200
	v_and_b32_e32 v200, 0xffff0000, v200
	v_lshlrev_b32_e32 v145, 16, v201
	v_and_b32_e32 v201, 0xffff0000, v201
	v_mul_f32_e32 v86, v86, v142
	v_mul_f32_e32 v87, v87, v198
	v_mul_f32_e32 v88, v88, v143
	v_mul_f32_e32 v89, v89, v199
	v_mul_f32_e32 v82, v82, v144
	v_mul_f32_e32 v83, v83, v200
	v_mul_f32_e32 v84, v84, v145
	v_mul_f32_e32 v85, v85, v201
	v_cvt_pk_bf16_f32 v198, v86, v87
	v_cvt_pk_bf16_f32 v199, v88, v89
	v_cvt_pk_bf16_f32 v200, v82, v83
	v_cvt_pk_bf16_f32 v201, v84, v85
	s_waitcnt vmcnt(9)
; __device__ __forceinline__ unsigned cvt_pk_bf16(float lo, float hi) { unsigned r; asm volatile("v_cvt_pk_bf16_f32 %0, %1, %2" : "=v"(r) : "v"(lo), "v"(hi)); return r; }
; __device__ __forceinline__ float bflo(unsigned w) { return __uint_as_float(w << 16); }
; __device__ __forceinline__ float bfhi(unsigned w) { return __uint_as_float(w & 0xffff0000u); }
;     __device__ __forceinline__ void operator()(const f32x4 (&acc)[2][2][4][2], const Unit& u, int wr, int wc, int fr, int fq) const {
;     ...
;             for (int m = 0; m < 4; ++m) { const size_t row = (size_t)(row0 + ai * HALF + m * 16);
; #pragma unroll
;                 for (int bj = 0; bj < 2; ++bj) { const int col = col0 + bj * HALF;
;                     const u32x4 g = *(const u32x4*)(P + row * LDP + PC_GB + col);
;                     f32x4 v0 = acc[ai][bj][m][0], v1 = acc[ai][bj][m][1];
;                     v0[0] *= bflo(g.x); v0[1] *= bfhi(g.x); v0[2] *= bflo(g.y); v0[3] *= bfhi(g.y);
;                     v1[0] *= bflo(g.z); v1[1] *= bfhi(g.z); v1[2] *= bflo(g.w); v1[3] *= bfhi(g.w);
;                     u32x4 w; w.x = cvt_pk_bf16(v0[0], v0[1]); w.y = cvt_pk_bf16(v0[2], v0[3]); w.z = cvt_pk_bf16(v1[0], v1[1]); w.w = cvt_pk_bf16(v1[2], v1[3]);
	v_lshlrev_b32_e32 v142, 16, v202
	v_and_b32_e32 v202, 0xffff0000, v202
	v_lshlrev_b32_e32 v143, 16, v203
	v_and_b32_e32 v203, 0xffff0000, v203
	v_lshlrev_b32_e32 v144, 16, v204
	v_and_b32_e32 v204, 0xffff0000, v204
	v_lshlrev_b32_e32 v145, 16, v205
	v_and_b32_e32 v205, 0xffff0000, v205
	v_mul_f32_e32 v78, v78, v142
	v_mul_f32_e32 v79, v79, v202
	v_mul_f32_e32 v80, v80, v143
	v_mul_f32_e32 v81, v81, v203
	v_mul_f32_e32 v74, v74, v144
	v_mul_f32_e32 v75, v75, v204
	v_mul_f32_e32 v76, v76, v145
	v_mul_f32_e32 v77, v77, v205
	v_cvt_pk_bf16_f32 v202, v78, v79
	v_cvt_pk_bf16_f32 v203, v80, v81
	v_cvt_pk_bf16_f32 v204, v74, v75
	v_cvt_pk_bf16_f32 v205, v76, v77
	s_waitcnt vmcnt(8)
	v_lshlrev_b32_e32 v142, 16, v206
	v_and_b32_e32 v206, 0xffff0000, v206
	v_lshlrev_b32_e32 v143, 16, v207
	v_and_b32_e32 v207, 0xffff0000, v207
	v_lshlrev_b32_e32 v144, 16, v208
	v_and_b32_e32 v208, 0xffff0000, v208
	v_lshlrev_b32_e32 v145, 16, v209
	v_and_b32_e32 v209, 0xffff0000, v209
	v_mul_f32_e32 v70, v70, v142
	v_mul_f32_e32 v71, v71, v206
	v_mul_f32_e32 v72, v72, v143
	v_mul_f32_e32 v73, v73, v207
	v_mul_f32_e32 v66, v66, v144
	v_mul_f32_e32 v67, v67, v208
	v_mul_f32_e32 v68, v68, v145
	v_mul_f32_e32 v69, v69, v209
	v_cvt_pk_bf16_f32 v206, v70, v71
	v_cvt_pk_bf16_f32 v207, v72, v73
	v_cvt_pk_bf16_f32 v208, v66, v67
	v_cvt_pk_bf16_f32 v209, v68, v69
	s_waitcnt vmcnt(7)
	v_lshlrev_b32_e32 v142, 16, v214
	v_and_b32_e32 v214, 0xffff0000, v214
	v_lshlrev_b32_e32 v143, 16, v215
	v_and_b32_e32 v215, 0xffff0000, v215
	v_lshlrev_b32_e32 v144, 16, v216
	v_and_b32_e32 v216, 0xffff0000, v216
	v_lshlrev_b32_e32 v145, 16, v217
	v_and_b32_e32 v217, 0xffff0000, v217
	v_mul_f32_e32 v62, v62, v142
	v_mul_f32_e32 v63, v63, v214
	v_mul_f32_e32 v64, v64, v143
	v_mul_f32_e32 v65, v65, v215
	v_mul_f32_e32 v58, v58, v144
	v_mul_f32_e32 v59, v59, v216
	v_mul_f32_e32 v60, v60, v145
	v_mul_f32_e32 v61, v61, v217
	v_cvt_pk_bf16_f32 v214, v62, v63
	v_cvt_pk_bf16_f32 v215, v64, v65
	v_cvt_pk_bf16_f32 v216, v58, v59
	v_cvt_pk_bf16_f32 v217, v60, v61
	s_waitcnt vmcnt(6)
	v_lshlrev_b32_e32 v142, 16, v218
	v_and_b32_e32 v218, 0xffff0000, v218
	v_lshlrev_b32_e32 v143, 16, v219
	v_and_b32_e32 v219, 0xffff0000, v219
	v_lshlrev_b32_e32 v144, 16, v220
	v_and_b32_e32 v220, 0xffff0000, v220
	v_lshlrev_b32_e32 v145, 16, v221
	v_and_b32_e32 v221, 0xffff0000, v221
	v_mul_f32_e32 v54, v54, v142
	v_mul_f32_e32 v55, v55, v218
	v_mul_f32_e32 v56, v56, v143
	v_mul_f32_e32 v57, v57, v219
	v_mul_f32_e32 v50, v50, v144
	v_mul_f32_e32 v51, v51, v220
	v_mul_f32_e32 v52, v52, v145
	v_mul_f32_e32 v53, v53, v221
	v_cvt_pk_bf16_f32 v218, v54, v55
	v_cvt_pk_bf16_f32 v219, v56, v57
	v_cvt_pk_bf16_f32 v220, v50, v51
	v_cvt_pk_bf16_f32 v221, v52, v53
	s_waitcnt vmcnt(5)
	v_lshlrev_b32_e32 v142, 16, v222
	v_and_b32_e32 v222, 0xffff0000, v222
	v_lshlrev_b32_e32 v143, 16, v223
	v_and_b32_e32 v223, 0xffff0000, v223
	v_lshlrev_b32_e32 v144, 16, v224
	v_and_b32_e32 v224, 0xffff0000, v224
	v_lshlrev_b32_e32 v145, 16, v225
	v_and_b32_e32 v225, 0xffff0000, v225
	v_mul_f32_e32 v46, v46, v142
	v_mul_f32_e32 v47, v47, v222
	v_mul_f32_e32 v48, v48, v143
	v_mul_f32_e32 v49, v49, v223
	v_mul_f32_e32 v42, v42, v144
	v_mul_f32_e32 v43, v43, v224
	v_mul_f32_e32 v44, v44, v145
	v_mul_f32_e32 v45, v45, v225
	v_cvt_pk_bf16_f32 v222, v46, v47
	v_cvt_pk_bf16_f32 v223, v48, v49
	v_cvt_pk_bf16_f32 v224, v42, v43
	v_cvt_pk_bf16_f32 v225, v44, v45
	s_waitcnt vmcnt(4)
	v_lshlrev_b32_e32 v142, 16, v226
	v_and_b32_e32 v226, 0xffff0000, v226
	v_lshlrev_b32_e32 v143, 16, v227
	v_and_b32_e32 v227, 0xffff0000, v227
	v_lshlrev_b32_e32 v144, 16, v228
	v_and_b32_e32 v228, 0xffff0000, v228
	v_lshlrev_b32_e32 v145, 16, v229
	v_and_b32_e32 v229, 0xffff0000, v229
	v_mul_f32_e32 v38, v38, v142
	v_mul_f32_e32 v39, v39, v226
	v_mul_f32_e32 v40, v40, v143
	v_mul_f32_e32 v41, v41, v227
	v_mul_f32_e32 v34, v34, v144
	v_mul_f32_e32 v35, v35, v228
	v_mul_f32_e32 v36, v36, v145
	v_mul_f32_e32 v37, v37, v229
	v_cvt_pk_bf16_f32 v226, v38, v39
	v_cvt_pk_bf16_f32 v227, v40, v41
	v_cvt_pk_bf16_f32 v228, v34, v35
	v_cvt_pk_bf16_f32 v229, v36, v37
	s_waitcnt vmcnt(3)
; __device__ __forceinline__ unsigned cvt_pk_bf16(float lo, float hi) { unsigned r; asm volatile("v_cvt_pk_bf16_f32 %0, %1, %2" : "=v"(r) : "v"(lo), "v"(hi)); return r; }
; __device__ __forceinline__ float bflo(unsigned w) { return __uint_as_float(w << 16); }
; __device__ __forceinline__ float bfhi(unsigned w) { return __uint_as_float(w & 0xffff0000u); }
;     __device__ __forceinline__ void operator()(const f32x4 (&acc)[2][2][4][2], const Unit& u, int wr, int wc, int fr, int fq) const {
;     ...
;             for (int m = 0; m < 4; ++m) { const size_t row = (size_t)(row0 + ai * HALF + m * 16);
; #pragma unroll
;                 for (int bj = 0; bj < 2; ++bj) { const int col = col0 + bj * HALF;
;                     const u32x4 g = *(const u32x4*)(P + row * LDP + PC_GB + col);
;                     f32x4 v0 = acc[ai][bj][m][0], v1 = acc[ai][bj][m][1];
;                     v0[0] *= bflo(g.x); v0[1] *= bfhi(g.x); v0[2] *= bflo(g.y); v0[3] *= bfhi(g.y);
;                     v1[0] *= bflo(g.z); v1[1] *= bfhi(g.z); v1[2] *= bflo(g.w); v1[3] *= bfhi(g.w);
;                     u32x4 w; w.x = cvt_pk_bf16(v0[0], v0[1]); w.y = cvt_pk_bf16(v0[2], v0[3]); w.z = cvt_pk_bf16(v1[0], v1[1]); w.w = cvt_pk_bf16(v1[2], v1[3]);
;                     *(u32x4*)(O + row * 2048 + col) = w; }
;                 asm volatile("" ::: "memory"); }
;     }
	v_lshlrev_b32_e32 v142, 16, v230
	v_and_b32_e32 v230, 0xffff0000, v230
	v_lshlrev_b32_e32 v143, 16, v231
	v_and_b32_e32 v231, 0xffff0000, v231
	v_lshlrev_b32_e32 v144, 16, v232
	v_and_b32_e32 v232, 0xffff0000, v232
	v_lshlrev_b32_e32 v145, 16, v233
	v_and_b32_e32 v233, 0xffff0000, v233
	v_mul_f32_e32 v30, v30, v142
	v_mul_f32_e32 v31, v31, v230
	v_mul_f32_e32 v32, v32, v143
	v_mul_f32_e32 v33, v33, v231
	v_mul_f32_e32 v26, v26, v144
	v_mul_f32_e32 v27, v27, v232
	v_mul_f32_e32 v28, v28, v145
	v_mul_f32_e32 v29, v29, v233
	v_cvt_pk_bf16_f32 v230, v30, v31
	v_cvt_pk_bf16_f32 v231, v32, v33
	v_cvt_pk_bf16_f32 v232, v26, v27
	v_cvt_pk_bf16_f32 v233, v28, v29
	s_waitcnt vmcnt(2)
	v_lshlrev_b32_e32 v142, 16, v234
	v_and_b32_e32 v234, 0xffff0000, v234
	v_lshlrev_b32_e32 v143, 16, v235
	v_and_b32_e32 v235, 0xffff0000, v235
	v_lshlrev_b32_e32 v144, 16, v236
	v_and_b32_e32 v236, 0xffff0000, v236
	v_lshlrev_b32_e32 v145, 16, v237
	v_and_b32_e32 v237, 0xffff0000, v237
	v_mul_f32_e32 v22, v22, v142
	v_mul_f32_e32 v23, v23, v234
	v_mul_f32_e32 v24, v24, v143
	v_mul_f32_e32 v25, v25, v235
	v_mul_f32_e32 v18, v18, v144
	v_mul_f32_e32 v19, v19, v236
	v_mul_f32_e32 v20, v20, v145
	v_mul_f32_e32 v21, v21, v237
	v_cvt_pk_bf16_f32 v234, v22, v23
	v_cvt_pk_bf16_f32 v235, v24, v25
	v_cvt_pk_bf16_f32 v236, v18, v19
	v_cvt_pk_bf16_f32 v237, v20, v21
	s_waitcnt vmcnt(1)
	v_lshlrev_b32_e32 v142, 16, v238
	v_and_b32_e32 v238, 0xffff0000, v238
	v_lshlrev_b32_e32 v143, 16, v239
	v_and_b32_e32 v239, 0xffff0000, v239
	v_lshlrev_b32_e32 v144, 16, v240
	v_and_b32_e32 v240, 0xffff0000, v240
	v_lshlrev_b32_e32 v145, 16, v241
	v_and_b32_e32 v241, 0xffff0000, v241
	v_mul_f32_e32 v14, v14, v142
	v_mul_f32_e32 v15, v15, v238
	v_mul_f32_e32 v16, v16, v143
	v_mul_f32_e32 v17, v17, v239
	v_mul_f32_e32 v10, v10, v144
	v_mul_f32_e32 v11, v11, v240
	v_mul_f32_e32 v12, v12, v145
	v_mul_f32_e32 v13, v13, v241
	v_cvt_pk_bf16_f32 v238, v14, v15
	v_cvt_pk_bf16_f32 v239, v16, v17
	v_cvt_pk_bf16_f32 v240, v10, v11
	v_cvt_pk_bf16_f32 v241, v12, v13
	s_waitcnt vmcnt(0)
	v_lshlrev_b32_e32 v142, 16, v242
	v_and_b32_e32 v242, 0xffff0000, v242
	v_lshlrev_b32_e32 v143, 16, v243
	v_and_b32_e32 v243, 0xffff0000, v243
	v_lshlrev_b32_e32 v144, 16, v244
	v_and_b32_e32 v244, 0xffff0000, v244
	v_lshlrev_b32_e32 v145, 16, v245
	v_and_b32_e32 v245, 0xffff0000, v245
	v_mul_f32_e32 v6, v6, v142
	v_mul_f32_e32 v7, v7, v242
	v_mul_f32_e32 v8, v8, v143
	v_mul_f32_e32 v9, v9, v243
	v_mul_f32_e32 v2, v2, v144
	v_mul_f32_e32 v3, v3, v244
	v_mul_f32_e32 v4, v4, v145
	v_mul_f32_e32 v5, v5, v245
	v_cvt_pk_bf16_f32 v242, v6, v7
	v_cvt_pk_bf16_f32 v243, v8, v9
	v_cvt_pk_bf16_f32 v244, v2, v3
	v_cvt_pk_bf16_f32 v245, v4, v5
	global_store_dwordx4 v163, v[130:133], s[42:43]
	s_add_u32 s2, s42, 0x100
	s_addc_u32 s3, s43, 0
	global_store_dwordx4 v163, v[134:137], s[2:3]
	s_add_u32 s2, s42, 0x10000
	s_addc_u32 s3, s43, 0
	global_store_dwordx4 v163, v[186:189], s[2:3]
	s_add_u32 s2, s42, 0x10100
	s_addc_u32 s3, s43, 0
	global_store_dwordx4 v163, v[190:193], s[2:3]
	s_add_u32 s2, s42, 0x20000
	s_addc_u32 s3, s43, 0
	global_store_dwordx4 v163, v[194:197], s[2:3]
	s_add_u32 s2, s42, 0x20100
	s_addc_u32 s3, s43, 0
	global_store_dwordx4 v163, v[198:201], s[2:3]
	s_add_u32 s2, s42, 0x30000
	s_addc_u32 s3, s43, 0
	global_store_dwordx4 v163, v[202:205], s[2:3]
	s_add_u32 s2, s42, 0x30100
	s_addc_u32 s3, s43, 0
	global_store_dwordx4 v163, v[206:209], s[2:3]
	s_add_u32 s2, s42, 0x80000
	s_addc_u32 s3, s43, 0
	global_store_dwordx4 v163, v[214:217], s[2:3]
	s_add_u32 s2, s42, 0x80100
	s_addc_u32 s3, s43, 0
	global_store_dwordx4 v163, v[218:221], s[2:3]
	s_add_u32 s2, s42, 0x90000
	s_addc_u32 s3, s43, 0
	global_store_dwordx4 v163, v[222:225], s[2:3]
	s_add_u32 s2, s42, 0x90100
	s_addc_u32 s3, s43, 0
	global_store_dwordx4 v163, v[226:229], s[2:3]
	s_add_u32 s2, s42, 0xa0000
	s_addc_u32 s3, s43, 0
	global_store_dwordx4 v163, v[230:233], s[2:3]
	s_add_u32 s2, s42, 0xa0100
	s_addc_u32 s3, s43, 0
	global_store_dwordx4 v163, v[234:237], s[2:3]
	s_add_u32 s2, s42, 0xb0000
	s_addc_u32 s3, s43, 0
	global_store_dwordx4 v163, v[238:241], s[2:3]
	s_add_u32 s2, s42, 0xb0100
	s_addc_u32 s3, s43, 0
	global_store_dwordx4 v163, v[242:245], s[2:3]
	s_mov_b64 s[2:3], -1
	s_andn2_b64 vcc, exec, s[38:39]
	s_cbranch_vccnz .LBB0_69
	s_andn2_b64 vcc, exec, s[0:1]
	s_cbranch_vccnz .LBB0_68
	s_barrier
	s_branch .LBB0_68
